# attention steady loop: first QK MFMA issued after the C0 subs, C1 subs and G prefetch in its shadow (on top of v11 G-prefetch)
# speedup vs baseline: 1.0012x; 1.0012x over previous
.LBB0_1341:
	v_sub_f32_e32 v181, v214, v217
	s_waitcnt lgkmcnt(4)
	v_sub_f32_e32 v111, v181, v223
	v_sub_f32_e32 v110, v181, v222
	v_sub_f32_e32 v109, v181, v221
	v_sub_f32_e32 v108, v181, v220
	v_sub_f32_e32 v107, v181, v199
	v_sub_f32_e32 v106, v181, v198
	v_sub_f32_e32 v105, v181, v197
	v_sub_f32_e32 v104, v181, v196
	v_sub_f32_e32 v103, v181, v195
	v_sub_f32_e32 v102, v181, v194
	v_sub_f32_e32 v101, v181, v193
	v_sub_f32_e32 v100, v181, v192
	v_sub_f32_e32 v99, v181, v191
	v_sub_f32_e32 v98, v181, v190
	v_sub_f32_e32 v97, v181, v189
	v_sub_f32_e32 v96, v181, v188
	v_add_u32_e32 v0, s8, v216
	ds_read_b64_tr_b16 v[4:5], v0 offset:24576
	ds_read_b64_tr_b16 v[6:7], v0 offset:25088
	v_mfma_f32_32x32x16_bf16 v[96:111], v[172:175], v[124:127], v[96:111]
	s_waitcnt lgkmcnt(2)
	v_sub_f32_e32 v95, v181, v239
	v_sub_f32_e32 v94, v181, v238
	v_sub_f32_e32 v93, v181, v237
	v_sub_f32_e32 v92, v181, v236
	v_sub_f32_e32 v91, v181, v235
	v_sub_f32_e32 v90, v181, v234
	v_sub_f32_e32 v89, v181, v233
	v_sub_f32_e32 v88, v181, v232
	v_sub_f32_e32 v87, v181, v231
	v_sub_f32_e32 v86, v181, v230
	v_sub_f32_e32 v85, v181, v229
	v_sub_f32_e32 v84, v181, v228
	v_sub_f32_e32 v83, v181, v227
	v_sub_f32_e32 v82, v181, v226
	v_sub_f32_e32 v81, v181, v225
	v_sub_f32_e32 v80, v181, v224
	ds_read_b128 v[188:191], v180 offset:256
	ds_read_b128 v[192:195], v180 offset:288
	ds_read_b128 v[196:199], v180 offset:320
	ds_read_b128 v[220:223], v180 offset:352
	ds_read_b128 v[224:227], v180 offset:384
	ds_read_b128 v[228:231], v180 offset:416
	ds_read_b128 v[232:235], v180 offset:448
	ds_read_b128 v[236:239], v180 offset:480
	v_add_f32_e32 v1, v64, v65
	v_add_f32_e32 v1, v66, v1
	v_add_f32_e32 v1, v67, v1
	v_add_f32_e32 v1, v68, v1
	v_add_f32_e32 v1, v69, v1
	v_cvt_pk_bf16_f32 v140, v64, v65
	v_cvt_pk_bf16_f32 v141, v66, v67
	ds_read_b64_tr_b16 v[8:9], v0 offset:28672
	ds_read_b64_tr_b16 v[10:11], v0 offset:29184
	v_mfma_f32_32x32x16_bf16 v[80:95], v[168:171], v[124:127], v[80:95]
	v_add_f32_e32 v1, v70, v1
	v_add_f32_e32 v1, v71, v1
	v_add_f32_e32 v1, v72, v1
	v_add_f32_e32 v1, v73, v1
	v_cvt_pk_bf16_f32 v142, v68, v69
	v_cvt_pk_bf16_f32 v143, v70, v71
	ds_read_b64_tr_b16 v[12:13], v0 offset:25600
	ds_read_b64_tr_b16 v[14:15], v0 offset:26112
	v_mfma_f32_32x32x16_bf16 v[96:111], v[164:167], v[120:123], v[96:111]
	v_add_f32_e32 v1, v74, v1
	v_add_f32_e32 v1, v75, v1
	v_add_f32_e32 v1, v76, v1
	v_add_f32_e32 v1, v77, v1
	v_cvt_pk_bf16_f32 v136, v72, v73
	v_cvt_pk_bf16_f32 v137, v74, v75
	ds_read_b64_tr_b16 v[64:65], v0 offset:29696
	ds_read_b64_tr_b16 v[66:67], v0 offset:30208
	v_mfma_f32_32x32x16_bf16 v[80:95], v[160:163], v[120:123], v[80:95]
	v_add_f32_e32 v1, v78, v1
	v_add_f32_e32 v1, v79, v1
	v_add_f32_e32 v1, v48, v1
	v_add_f32_e32 v1, v49, v1
	v_cvt_pk_bf16_f32 v138, v76, v77
	v_cvt_pk_bf16_f32 v139, v78, v79
	ds_read_b64_tr_b16 v[68:69], v0 offset:26624
	ds_read_b64_tr_b16 v[70:71], v0 offset:27136
	v_mfma_f32_32x32x16_bf16 v[96:111], v[156:159], v[116:119], v[96:111]
	v_add_f32_e32 v1, v50, v1
	v_add_f32_e32 v1, v51, v1
	v_add_f32_e32 v1, v52, v1
	v_add_f32_e32 v1, v53, v1
	v_cvt_pk_bf16_f32 v132, v48, v49
	v_cvt_pk_bf16_f32 v133, v50, v51
	ds_read_b64_tr_b16 v[48:49], v0 offset:30720
	ds_read_b64_tr_b16 v[50:51], v0 offset:31232
	v_mfma_f32_32x32x16_bf16 v[80:95], v[152:155], v[116:119], v[80:95]
	v_add_f32_e32 v1, v54, v1
	v_add_f32_e32 v1, v55, v1
	v_add_f32_e32 v1, v56, v1
	v_add_f32_e32 v1, v57, v1
	v_cvt_pk_bf16_f32 v134, v52, v53
	v_cvt_pk_bf16_f32 v135, v54, v55
	ds_read_b64_tr_b16 v[52:53], v0 offset:27648
	ds_read_b64_tr_b16 v[54:55], v0 offset:28160
	v_mfma_f32_32x32x16_bf16 v[96:111], v[148:151], v[112:115], v[96:111]
	v_add_f32_e32 v1, v58, v1
	v_add_f32_e32 v1, v59, v1
	v_add_f32_e32 v1, v60, v1
	v_add_f32_e32 v1, v61, v1
	v_cvt_pk_bf16_f32 v128, v56, v57
	v_cvt_pk_bf16_f32 v129, v58, v59
	ds_read_b64_tr_b16 v[56:57], v0 offset:31744
	ds_read_b64_tr_b16 v[58:59], v0 offset:32256
	v_mfma_f32_32x32x16_bf16 v[80:95], v[144:147], v[112:115], v[80:95]
	v_add_f32_e32 v0, v62, v1
	v_add_f32_e32 v0, v63, v0
	v_add_f32_e32 v2, 0, v0
	v_cvt_pk_bf16_f32 v130, v60, v61
	v_cvt_pk_bf16_f32 v131, v62, v63
	s_mov_b32 s8, 0xfffe0000
	s_mov_b32 s9, -1
	v_lshl_add_u64 v[0:1], v[178:179], 0, s[8:9]
	s_add_i32 s0, s16, s21
	s_mov_b32 s4, m0
	s_mov_b32 m0, s0
	s_nop 0
	global_load_lds_dwordx4 v[0:1], off
	s_mov_b32 m0, s4
	v_lshl_add_u64 v[0:1], v[176:177], 0, s[8:9]
	s_add_i32 s0, s14, s22
	s_mov_b32 s4, m0
	s_mov_b32 m0, s0
	s_nop 0
	global_load_lds_dwordx4 v[0:1], off
	s_mov_b32 m0, s4
	v_max_f32_e32 v0, v97, v97
	v_max_f32_e32 v1, v96, v96
	v_max_f32_e32 v0, v1, v0
	v_max3_f32 v1, v98, v99, v81
	v_max3_f32 v0, v0, v80, v82
	v_max3_f32 v0, v0, v83, v100
	v_max3_f32 v1, v1, v102, v103
	v_max3_f32 v0, v0, v101, v84
	v_max3_f32 v1, v1, v86, v87
	v_max3_f32 v0, v0, v85, v104
	v_max3_f32 v1, v1, v106, v107
	v_max3_f32 v0, v0, v105, v88
	v_max3_f32 v1, v1, v90, v91
	v_max3_f32 v0, v0, v89, v108
	v_max3_f32 v1, v1, v110, v111
	v_max3_f32 v60, v0, v109, v92
	v_max3_f32 v1, v1, v94, v95
	v_max3_f32 v1, v60, v93, v1
	v_add_f32_e32 v0, v218, v2
	v_mov_b32_e32 v2, v1
	s_nop 1
	v_permlane32_swap_b32_e32 v1, v2
	v_max_f32_e32 v2, v2, v2
	v_max_f32_e32 v1, v1, v1
	v_max_f32_e32 v1, v1, v2
	v_cmp_lt_f32_e32 vcc, s33, v1
	s_cmp_lg_u64 vcc, 0
	s_cselect_b64 s[8:9], -1, 0
	s_cbranch_vccnz .LBB0_1349

.LBB0_1344:
	s_add_i32 s0, s14, 0x2000
	s_cmpk_lg_i32 s14, 0x4000
	s_cselect_b32 s25, s0, 0
	v_sub_f32_e32 v181, v214, v217
	s_waitcnt lgkmcnt(4)
	v_sub_f32_e32 v79, v181, v223
	v_sub_f32_e32 v78, v181, v222
	v_sub_f32_e32 v77, v181, v221
	v_sub_f32_e32 v76, v181, v220
	v_sub_f32_e32 v75, v181, v199
	v_sub_f32_e32 v74, v181, v198
	v_sub_f32_e32 v73, v181, v197
	v_sub_f32_e32 v72, v181, v196
	v_sub_f32_e32 v71, v181, v195
	v_sub_f32_e32 v70, v181, v194
	v_sub_f32_e32 v69, v181, v193
	v_sub_f32_e32 v68, v181, v192
	v_sub_f32_e32 v67, v181, v191
	v_sub_f32_e32 v66, v181, v190
	v_sub_f32_e32 v65, v181, v189
	v_sub_f32_e32 v64, v181, v188
	v_add_u32_e32 v1, s16, v216
	ds_read_b64_tr_b16 v[152:153], v1 offset:24576
	ds_read_b64_tr_b16 v[154:155], v1 offset:25088
	v_mfma_f32_32x32x16_bf16 v[64:79], v[164:167], v[124:127], v[64:79]
	s_waitcnt lgkmcnt(2)
	v_sub_f32_e32 v63, v181, v239
	v_sub_f32_e32 v62, v181, v238
	v_sub_f32_e32 v61, v181, v237
	v_sub_f32_e32 v60, v181, v236
	v_sub_f32_e32 v59, v181, v235
	v_sub_f32_e32 v58, v181, v234
	v_sub_f32_e32 v57, v181, v233
	v_sub_f32_e32 v56, v181, v232
	v_sub_f32_e32 v55, v181, v231
	v_sub_f32_e32 v54, v181, v230
	v_sub_f32_e32 v53, v181, v229
	v_sub_f32_e32 v52, v181, v228
	v_sub_f32_e32 v51, v181, v227
	v_sub_f32_e32 v50, v181, v226
	v_sub_f32_e32 v49, v181, v225
	v_sub_f32_e32 v48, v181, v224
	ds_read_b128 v[188:191], v180 offset:512
	ds_read_b128 v[192:195], v180 offset:544
	ds_read_b128 v[196:199], v180 offset:576
	ds_read_b128 v[220:223], v180 offset:608
	ds_read_b128 v[224:227], v180 offset:640
	ds_read_b128 v[228:231], v180 offset:672
	ds_read_b128 v[232:235], v180 offset:704
	ds_read_b128 v[236:239], v180 offset:736
	v_add_f32_e32 v2, v96, v97
	v_add_f32_e32 v2, v98, v2
	v_add_f32_e32 v2, v99, v2
	v_add_f32_e32 v2, v100, v2
	v_add_f32_e32 v2, v101, v2
	v_cvt_pk_bf16_f32 v140, v96, v97
	v_cvt_pk_bf16_f32 v141, v98, v99
	ds_read_b64_tr_b16 v[96:97], v1 offset:28672
	ds_read_b64_tr_b16 v[98:99], v1 offset:29184
	v_mfma_f32_32x32x16_bf16 v[48:63], v[160:163], v[124:127], v[48:63]
	v_add_f32_e32 v2, v102, v2
	v_add_f32_e32 v2, v103, v2
	v_add_f32_e32 v2, v104, v2
	v_add_f32_e32 v2, v105, v2
	v_cvt_pk_bf16_f32 v142, v100, v101
	v_cvt_pk_bf16_f32 v143, v102, v103
	ds_read_b64_tr_b16 v[100:101], v1 offset:25600
	ds_read_b64_tr_b16 v[102:103], v1 offset:26112
	v_mfma_f32_32x32x16_bf16 v[64:79], v[156:159], v[120:123], v[64:79]
	v_add_f32_e32 v2, v106, v2
	v_add_f32_e32 v2, v107, v2
	v_add_f32_e32 v2, v108, v2
	v_add_f32_e32 v2, v109, v2
	v_cvt_pk_bf16_f32 v136, v104, v105
	v_cvt_pk_bf16_f32 v137, v106, v107
	ds_read_b64_tr_b16 v[104:105], v1 offset:29696
	ds_read_b64_tr_b16 v[106:107], v1 offset:30208
	v_mfma_f32_32x32x16_bf16 v[48:63], v[148:151], v[120:123], v[48:63]
	v_add_f32_e32 v2, v110, v2
	v_add_f32_e32 v2, v111, v2
	v_add_f32_e32 v2, v80, v2
	v_add_f32_e32 v2, v81, v2
	v_cvt_pk_bf16_f32 v138, v108, v109
	v_cvt_pk_bf16_f32 v139, v110, v111
	ds_read_b64_tr_b16 v[108:109], v1 offset:26624
	ds_read_b64_tr_b16 v[110:111], v1 offset:27136
	v_mfma_f32_32x32x16_bf16 v[64:79], v[144:147], v[116:119], v[64:79]
	v_add_f32_e32 v2, v82, v2
	v_add_f32_e32 v2, v83, v2
	v_add_f32_e32 v2, v84, v2
	v_add_f32_e32 v2, v85, v2
	v_cvt_pk_bf16_f32 v132, v80, v81
	v_cvt_pk_bf16_f32 v133, v82, v83
	ds_read_b64_tr_b16 v[80:81], v1 offset:30720
	ds_read_b64_tr_b16 v[82:83], v1 offset:31232
	v_mfma_f32_32x32x16_bf16 v[48:63], v[12:15], v[116:119], v[48:63]
	v_add_f32_e32 v2, v86, v2
	v_add_f32_e32 v2, v87, v2
	v_add_f32_e32 v2, v88, v2
	v_add_f32_e32 v2, v89, v2
	v_cvt_pk_bf16_f32 v134, v84, v85
	v_cvt_pk_bf16_f32 v135, v86, v87
	ds_read_b64_tr_b16 v[12:13], v1 offset:27648
	ds_read_b64_tr_b16 v[14:15], v1 offset:28160
	v_mfma_f32_32x32x16_bf16 v[64:79], v[8:11], v[112:115], v[64:79]
	v_add_f32_e32 v2, v90, v2
	v_add_f32_e32 v2, v91, v2
	v_add_f32_e32 v2, v92, v2
	v_add_f32_e32 v2, v93, v2
	v_cvt_pk_bf16_f32 v128, v88, v89
	v_cvt_pk_bf16_f32 v129, v90, v91
	ds_read_b64_tr_b16 v[8:9], v1 offset:31744
	ds_read_b64_tr_b16 v[10:11], v1 offset:32256
	v_mfma_f32_32x32x16_bf16 v[48:63], v[4:7], v[112:115], v[48:63]
	v_add_f32_e32 v1, v94, v2
	v_add_f32_e32 v1, v95, v1
	v_add_f32_e32 v1, 0, v1
	v_cvt_pk_bf16_f32 v130, v92, v93
	v_cvt_pk_bf16_f32 v131, v94, v95
	v_max_f32_e32 v2, v65, v65
	v_max_f32_e32 v4, v64, v64
	v_max_f32_e32 v2, v4, v2
	s_nop 3
	v_max3_f32 v4, v66, v67, v49
	v_max3_f32 v2, v2, v48, v50
	v_max3_f32 v2, v2, v51, v68
	v_max3_f32 v4, v4, v70, v71
	v_max3_f32 v2, v2, v69, v52
	v_max3_f32 v4, v4, v54, v55
	v_max3_f32 v2, v2, v53, v72
	v_max3_f32 v4, v4, v74, v75
	v_max3_f32 v2, v2, v73, v56
	v_max3_f32 v4, v4, v58, v59
	v_max3_f32 v2, v2, v57, v76
	v_max3_f32 v4, v4, v78, v79
	v_max3_f32 v2, v2, v77, v60
	v_max3_f32 v4, v4, v62, v63
	v_add_f32_e32 v218, v0, v1
	v_max3_f32 v0, v2, v61, v4
	v_mov_b32_e32 v1, v0
	s_nop 1
	v_permlane32_swap_b32_e32 v0, v1
	v_max_f32_e32 v1, v1, v1
	v_max_f32_e32 v0, v0, v0
	s_add_i32 s0, s14, s21
	s_mov_b32 s4, m0
	s_mov_b32 m0, s0
	s_nop 0
	global_load_lds_dwordx4 v[178:179], off
	s_mov_b32 m0, s4
	v_max_f32_e32 v0, v0, v1
	s_add_i32 s0, s25, s22
	s_mov_b32 s4, m0
	s_mov_b32 m0, s0
	s_nop 0
	global_load_lds_dwordx4 v[176:177], off
	s_mov_b32 m0, s4
	v_cmp_lt_f32_e32 vcc, s33, v0
	s_cmp_lg_u64 vcc, 0
	s_cselect_b64 s[8:9], -1, 0
	s_cbranch_vccnz .LBB0_1352
